# final RMSNorm: row-invariant gain chunks loaded once before the row loop (removes 8 serialized load->vmcnt(0)->store steps per row)
# speedup vs baseline: 1.0032x; 1.0032x over previous
.LBB0_187:
	v_mov_b32_e32 v154, v206
	v_readlane_b32 s84, v253, 0
	s_mov_b64 s[0:1], 0
	s_add_u32 s24, s10, s0
	s_addc_u32 s25, s11, s1
	s_lshl_b64 s[0:1], s[0:1], 2
	s_add_u32 s4, s8, s0
	s_addc_u32 s5, s9, s1
	s_mov_b64 s[6:7], -1
	s_mov_b64 s[0:1], 0
	s_cmp_lt_i32 s12, 17
	s_mov_b64 s[2:3], 0
	s_cbranch_scc1 .LBB0_204
	s_cmp_eq_u32 s12, 17
	s_mov_b64 s[2:3], -1
	s_cbranch_scc0 .LBB0_193
	v_ashrrev_i32_e32 v0, 6, v154
	s_waitcnt lgkmcnt(0)
	v_lshl_add_u32 v2, s84, 3, v0
	s_mov_b32 s2, 0x8000
	v_cmp_gt_i32_e32 vcc, s2, v2
	s_and_saveexec_b64 s[2:3], vcc
	s_cbranch_execz .LBB0_192
	v_cmp_lt_i32_e32 vcc, v211, v210
	s_waitcnt vmcnt(0)
	v_and_b32_e32 v20, 63, v154
	v_readlane_b32 s6, v253, 60
	v_cndmask_b32_e32 v0, v209, v211, vcc
	v_cmp_lt_i32_e32 vcc, v212, v210
	v_lshlrev_b32_e32 v28, 2, v0
	v_readlane_b32 s7, v253, 61
	v_cndmask_b32_e32 v0, v209, v212, vcc
	v_cmp_lt_i32_e32 vcc, v213, v210
	v_lshlrev_b32_e32 v29, 2, v0
	v_or_b32_e32 v22, 0x100, v20
	v_cndmask_b32_e32 v0, v209, v213, vcc
	v_cmp_lt_i32_e32 vcc, v214, v210
	v_lshlrev_b32_e32 v30, 2, v0
	v_or_b32_e32 v24, 0x140, v20
	v_cndmask_b32_e32 v0, v209, v214, vcc
	v_cmp_lt_i32_e32 vcc, v215, v210
	v_lshlrev_b32_e32 v31, 2, v0
	v_or_b32_e32 v26, 0x180, v20
	v_cndmask_b32_e32 v0, v209, v215, vcc
	v_cmp_lt_i32_e32 vcc, v216, v210
	v_lshlrev_b32_e32 v32, 2, v0
	v_or_b32_e32 v34, 0x1c0, v20
	v_cndmask_b32_e32 v0, v209, v216, vcc
	v_lshlrev_b32_e32 v33, 2, v0
	v_lshlrev_b32_e32 v0, 4, v20
	v_lshl_add_u64 v[4:5], s[6:7], 0, v[0:1]
	v_or_b32_e32 v6, 0x400, v0
	v_or_b32_e32 v8, 0x800, v0
	v_or_b32_e32 v0, 0xc00, v0
	v_lshl_add_u64 v[10:11], s[6:7], 0, v[0:1]
	v_lshlrev_b32_e32 v0, 4, v22
	v_lshl_add_u64 v[12:13], s[6:7], 0, v[0:1]
	v_lshlrev_b32_e32 v0, 4, v24
	v_lshl_add_u64 v[14:15], s[6:7], 0, v[0:1]
	v_lshlrev_b32_e32 v0, 4, v26
	v_mov_b32_e32 v7, v1
	v_mov_b32_e32 v9, v1
	v_lshl_add_u64 v[16:17], s[6:7], 0, v[0:1]
	v_lshlrev_b32_e32 v0, 4, v34
	v_lshl_add_u64 v[6:7], s[6:7], 0, v[6:7]
	v_lshl_add_u64 v[8:9], s[6:7], 0, v[8:9]
	v_lshl_add_u64 v[18:19], s[6:7], 0, v[0:1]
	s_mov_b64 s[6:7], 0
	v_lshlrev_b32_e32 v0, 4, v20
	v_lshlrev_b32_e32 v20, 4, v22
	v_mov_b32_e32 v21, v1
	v_lshlrev_b32_e32 v22, 4, v24
	v_mov_b32_e32 v23, v1
	v_lshlrev_b32_e32 v24, 4, v26
	v_mov_b32_e32 v25, v1
	v_lshlrev_b32_e32 v26, 4, v34
	v_mov_b32_e32 v27, v1
	global_load_dwordx4 v[100:103], v[4:5], off
	global_load_dwordx4 v[104:107], v[6:7], off
	global_load_dwordx4 v[108:111], v[8:9], off
	global_load_dwordx4 v[112:115], v[10:11], off
	global_load_dwordx4 v[116:119], v[12:13], off
	global_load_dwordx4 v[120:123], v[14:15], off
	global_load_dwordx4 v[124:127], v[16:17], off
	global_load_dwordx4 v[128:131], v[18:19], off
	s_waitcnt vmcnt(0)
.LBB0_191:
	v_ashrrev_i32_e32 v3, 31, v2
	v_lshlrev_b64 v[34:35], 13, v[2:3]
	v_lshl_add_u64 v[58:59], s[4:5], 0, v[34:35]
	v_lshl_add_u64 v[70:71], v[58:59], 0, v[0:1]
	v_lshl_add_u64 v[72:73], v[58:59], 0, v[20:21]
	global_load_dwordx4 v[34:37], v[70:71], off
	global_load_dwordx4 v[38:41], v[70:71], off offset:1024
	global_load_dwordx4 v[42:45], v[70:71], off offset:2048
	global_load_dwordx4 v[46:49], v[70:71], off offset:3072
	v_lshl_add_u64 v[74:75], v[58:59], 0, v[22:23]
	global_load_dwordx4 v[50:53], v[72:73], off
	global_load_dwordx4 v[54:57], v[74:75], off
	v_lshl_add_u64 v[76:77], v[58:59], 0, v[24:25]
	v_lshl_add_u64 v[78:79], v[58:59], 0, v[26:27]
	global_load_dwordx4 v[58:61], v[76:77], off
	global_load_dwordx4 v[62:65], v[78:79], off
	v_add_u32_e32 v2, s13, v2
	s_waitcnt vmcnt(7)
	v_mul_f32_e32 v3, v35, v35
	s_waitcnt vmcnt(6)
	v_mul_f32_e32 v96, v39, v39
	s_waitcnt vmcnt(5)
	v_mul_f32_e32 v97, v43, v43
	v_fmac_f32_e32 v3, v34, v34
	v_fmac_f32_e32 v96, v38, v38
	s_waitcnt vmcnt(4)
	v_mul_f32_e32 v98, v47, v47
	s_waitcnt vmcnt(3)
	v_mov_b32_e32 v82, v51
	s_waitcnt vmcnt(2)
	v_mov_b32_e32 v83, v55
	v_fmac_f32_e32 v97, v42, v42
	v_fmac_f32_e32 v3, v36, v36
	v_fmac_f32_e32 v96, v40, v40
	v_mov_b32_e32 v80, v50
	v_mov_b32_e32 v81, v54
	v_fmac_f32_e32 v98, v46, v46
	v_pk_mul_f32 v[82:83], v[82:83], v[82:83]
	v_fmac_f32_e32 v97, v44, v44
	v_fmac_f32_e32 v3, v37, v37
	v_fmac_f32_e32 v96, v41, v41
	v_mov_b32_e32 v84, v52
	v_mov_b32_e32 v85, v56
	s_waitcnt vmcnt(1)
	v_mov_b32_e32 v90, v59
	s_waitcnt vmcnt(0)
	v_mov_b32_e32 v91, v63
	v_fmac_f32_e32 v98, v48, v48
	v_pk_fma_f32 v[80:81], v[80:81], v[80:81], v[82:83]
	v_fmac_f32_e32 v97, v45, v45
	v_add_f32_e32 v3, v3, v96
	v_mov_b32_e32 v86, v53
	v_mov_b32_e32 v87, v57
	v_mov_b32_e32 v88, v58
	v_mov_b32_e32 v89, v62
	v_pk_mul_f32 v[90:91], v[90:91], v[90:91]
	v_fmac_f32_e32 v98, v49, v49
	v_pk_fma_f32 v[80:81], v[84:85], v[84:85], v[80:81]
	v_add_f32_e32 v3, v3, v97
	v_mov_b32_e32 v92, v60
	v_mov_b32_e32 v93, v64
	v_pk_fma_f32 v[82:83], v[88:89], v[88:89], v[90:91]
	v_pk_fma_f32 v[80:81], v[86:87], v[86:87], v[80:81]
	v_add_f32_e32 v3, v3, v98
	v_mov_b32_e32 v94, v61
	v_mov_b32_e32 v95, v65
	v_pk_fma_f32 v[82:83], v[92:93], v[92:93], v[82:83]
	v_add_f32_e32 v3, v3, v80
	v_pk_fma_f32 v[82:83], v[94:95], v[94:95], v[82:83]
	v_add_f32_e32 v3, v3, v81
	v_add_f32_e32 v3, v3, v82
	v_add_f32_e32 v3, v3, v83
	ds_bpermute_b32 v80, v28, v3
	s_waitcnt lgkmcnt(0)
	v_add_f32_e32 v3, v3, v80
	ds_bpermute_b32 v80, v29, v3
	s_waitcnt lgkmcnt(0)
	v_add_f32_e32 v3, v3, v80
	ds_bpermute_b32 v80, v30, v3
	s_waitcnt lgkmcnt(0)
	v_add_f32_e32 v3, v3, v80
	ds_bpermute_b32 v80, v31, v3
	s_waitcnt lgkmcnt(0)
	v_add_f32_e32 v3, v3, v80
	ds_bpermute_b32 v80, v32, v3
	s_waitcnt lgkmcnt(0)
	v_add_f32_e32 v3, v3, v80
	ds_bpermute_b32 v80, v33, v3
	s_waitcnt lgkmcnt(0)
	v_add_f32_e32 v3, v3, v80
	v_fmamk_f32 v3, v3, 0x3a000000, v207
	v_mul_f32_e32 v80, 0x4b800000, v3
	v_cmp_gt_f32_e32 vcc, s33, v3
	s_nop 1
	v_cndmask_b32_e32 v3, v3, v80, vcc
	v_rsq_f32_e32 v3, v3
	s_nop 0
	v_mul_f32_e32 v80, 0x45800000, v3
	v_cndmask_b32_e32 v80, v3, v80, vcc
	v_pk_mul_f32 v[34:35], v[34:35], v[80:81] op_sel_hi:[1,0]
	v_pk_mul_f32 v[36:37], v[36:37], v[80:81] op_sel_hi:[1,0]
	v_pk_mul_f32 v[34:35], v[100:101], v[34:35]
	v_pk_mul_f32 v[36:37], v[102:103], v[36:37]
	global_store_dwordx4 v[70:71], v[34:37], off
	v_pk_mul_f32 v[40:41], v[40:41], v[80:81] op_sel_hi:[1,0]
	v_pk_mul_f32 v[38:39], v[38:39], v[80:81] op_sel_hi:[1,0]
	v_cmp_lt_i32_e32 vcc, s97, v2
	s_or_b64 s[6:7], vcc, s[6:7]
	v_pk_mul_f32 v[34:35], v[104:105], v[38:39]
	v_pk_mul_f32 v[36:37], v[106:107], v[40:41]
	global_store_dwordx4 v[70:71], v[34:37], off offset:1024
	v_pk_mul_f32 v[38:39], v[44:45], v[80:81] op_sel_hi:[1,0]
	v_pk_mul_f32 v[40:41], v[42:43], v[80:81] op_sel_hi:[1,0]
	v_pk_mul_f32 v[36:37], v[110:111], v[38:39]
	v_pk_mul_f32 v[34:35], v[108:109], v[40:41]
	global_store_dwordx4 v[70:71], v[34:37], off offset:2048
	v_pk_mul_f32 v[38:39], v[48:49], v[80:81] op_sel_hi:[1,0]
	v_pk_mul_f32 v[40:41], v[46:47], v[80:81] op_sel_hi:[1,0]
	v_pk_mul_f32 v[36:37], v[114:115], v[38:39]
	v_pk_mul_f32 v[34:35], v[112:113], v[40:41]
	global_store_dwordx4 v[70:71], v[34:37], off offset:3072
	v_pk_mul_f32 v[38:39], v[52:53], v[80:81] op_sel_hi:[1,0]
	v_pk_mul_f32 v[40:41], v[50:51], v[80:81] op_sel_hi:[1,0]
	v_pk_mul_f32 v[36:37], v[118:119], v[38:39]
	v_pk_mul_f32 v[34:35], v[116:117], v[40:41]
	global_store_dwordx4 v[72:73], v[34:37], off
	v_pk_mul_f32 v[38:39], v[56:57], v[80:81] op_sel_hi:[1,0]
	v_pk_mul_f32 v[40:41], v[54:55], v[80:81] op_sel_hi:[1,0]
	v_pk_mul_f32 v[36:37], v[122:123], v[38:39]
	v_pk_mul_f32 v[34:35], v[120:121], v[40:41]
	global_store_dwordx4 v[74:75], v[34:37], off
	v_pk_mul_f32 v[38:39], v[60:61], v[80:81] op_sel_hi:[1,0]
	v_pk_mul_f32 v[40:41], v[58:59], v[80:81] op_sel_hi:[1,0]
	v_pk_mul_f32 v[36:37], v[126:127], v[38:39]
	v_pk_mul_f32 v[34:35], v[124:125], v[40:41]
	global_store_dwordx4 v[76:77], v[34:37], off
	v_pk_mul_f32 v[38:39], v[64:65], v[80:81] op_sel_hi:[1,0]
	v_pk_mul_f32 v[40:41], v[62:63], v[80:81] op_sel_hi:[1,0]
	v_pk_mul_f32 v[36:37], v[130:131], v[38:39]
	v_pk_mul_f32 v[34:35], v[128:129], v[40:41]
	global_store_dwordx4 v[78:79], v[34:37], off
	s_andn2_b64 exec, exec, s[6:7]
	s_cbranch_execnz .LBB0_191
